# v23 + non-temporal hint on the SwiGLU hidden-activation stores (written once, read once by the next phase)
# speedup vs baseline: 1.0104x; 1.0004x over previous
; __device__ __forceinline__ unsigned cvt_pk_bf16(float lo, float hi) { const f32x2 v = {lo, hi}; const pg8_bf16x2 b = __builtin_convertvector(v, pg8_bf16x2); return __builtin_bit_cast(unsigned, b); }
;     __device__ __forceinline__ void operator()(const f32x4 (&acc)[2][2][4][2], const Unit& u, int wr, int wc, int fr, int fq) const {
;         const int row0 = u.pm * BM + wr * 64 + fr;
;         float rs[2][4]; row_rstd(ss, row0, fq, rs);
; #pragma unroll
;         for (int ai = 0; ai < 2; ++ai)
; #pragma unroll
;             for (int m = 0; m < 4; ++m) {
;                 const float r = rs[ai][m]; f32x4 h[2];
; #pragma unroll
;                 for (int n = 0; n < 2; ++n) { const f32x4 g = acc[ai][0][m][n] * r, up = acc[ai][1][m][n] * r;
; #pragma unroll
;                     for (int i = 0; i < 4; ++i) h[n][i] = g[i] * up[i] * __builtin_amdgcn_rcpf(1.0f + __builtin_amdgcn_exp2f(-1.4426950408889634f * g[i])); }
;                 u32x4 w; w.x = cvt_pk_bf16(h[0][0], h[0][1]); w.y = cvt_pk_bf16(h[0][2], h[0][3]); w.z = cvt_pk_bf16(h[1][0], h[1][1]); w.w = cvt_pk_bf16(h[1][2], h[1][3]);
;                 *(u32x4*)(H + (size_t)(row0 + ai * HALF + m * 16) * 2816 + u.pn * HALF + wc * 32 + 8 * fq) = w;
.Lrstd_hit_gu:
	s_lshl_b32 s0, s51, 8
	s_lshl_b32 s1, s64, 1
	s_add_i32 s0, s0, s1
	s_movk_i32 s1, 0x1600
	v_lshlrev_b32_e32 v155, 1, v146
	v_mad_u32_u24 v155, v154, s1, v155
	v_add_u32_e32 v155, s0, v155
	v_mul_f32_e32 v126, v126, v248
	v_mul_f32_e32 v127, v127, v248
	v_mul_f32_e32 v128, v128, v248
	v_mul_f32_e32 v129, v129, v248
	v_mul_f32_e32 v122, v122, v248
	v_mul_f32_e32 v123, v123, v248
	v_mul_f32_e32 v124, v124, v248
	v_mul_f32_e32 v125, v125, v248
	v_mul_f32_e32 v172, 0xbfb8aa3b, v126
	v_mul_f32_e32 v173, 0xbfb8aa3b, v127
	v_mul_f32_e32 v174, 0xbfb8aa3b, v128
	v_mul_f32_e32 v175, 0xbfb8aa3b, v129
	v_exp_f32_e32 v172, v172
	v_exp_f32_e32 v173, v173
	v_exp_f32_e32 v174, v174
	v_exp_f32_e32 v175, v175
	v_mul_f32_e32 v122, v126, v122
	v_mul_f32_e32 v123, v127, v123
	v_mul_f32_e32 v124, v128, v124
	v_mul_f32_e32 v125, v129, v125
	v_add_f32_e32 v172, 1.0, v172
	v_add_f32_e32 v173, 1.0, v173
	v_add_f32_e32 v174, 1.0, v174
	v_add_f32_e32 v175, 1.0, v175
	v_rcp_f32_e32 v172, v172
	v_rcp_f32_e32 v173, v173
	v_rcp_f32_e32 v174, v174
	v_rcp_f32_e32 v175, v175
	v_mul_f32_e32 v126, v122, v172
	v_mul_f32_e32 v127, v123, v173
	v_mul_f32_e32 v128, v124, v174
	v_mul_f32_e32 v129, v125, v175
	v_mul_f32_e32 v118, v118, v248
	v_mul_f32_e32 v119, v119, v248
	v_mul_f32_e32 v120, v120, v248
	v_mul_f32_e32 v121, v121, v248
	v_mul_f32_e32 v114, v114, v248
	v_mul_f32_e32 v115, v115, v248
	v_mul_f32_e32 v116, v116, v248
	v_mul_f32_e32 v117, v117, v248
	v_mul_f32_e32 v172, 0xbfb8aa3b, v118
	v_mul_f32_e32 v173, 0xbfb8aa3b, v119
	v_mul_f32_e32 v174, 0xbfb8aa3b, v120
	v_mul_f32_e32 v175, 0xbfb8aa3b, v121
	v_exp_f32_e32 v172, v172
	v_exp_f32_e32 v173, v173
	v_exp_f32_e32 v174, v174
	v_exp_f32_e32 v175, v175
	v_mul_f32_e32 v114, v118, v114
	v_mul_f32_e32 v115, v119, v115
	v_mul_f32_e32 v116, v120, v116
	v_mul_f32_e32 v117, v121, v117
	v_add_f32_e32 v172, 1.0, v172
	v_add_f32_e32 v173, 1.0, v173
	v_add_f32_e32 v174, 1.0, v174
	v_add_f32_e32 v175, 1.0, v175
	v_rcp_f32_e32 v172, v172
	v_rcp_f32_e32 v173, v173
	v_rcp_f32_e32 v174, v174
	v_rcp_f32_e32 v175, v175
	v_mul_f32_e32 v118, v114, v172
	v_mul_f32_e32 v119, v115, v173
	v_mul_f32_e32 v120, v116, v174
	v_mul_f32_e32 v121, v117, v175
	v_cvt_pk_bf16_f32 v126, v126, v127
	v_cvt_pk_bf16_f32 v127, v128, v129
	v_cvt_pk_bf16_f32 v128, v118, v119
	v_cvt_pk_bf16_f32 v129, v120, v121
	global_store_dwordx4 v155, v[126:129], s[20:21] nt
	v_mul_f32_e32 v110, v110, v249
	v_mul_f32_e32 v111, v111, v249
	v_mul_f32_e32 v112, v112, v249
	v_mul_f32_e32 v113, v113, v249
	v_mul_f32_e32 v106, v106, v249
	v_mul_f32_e32 v107, v107, v249
	v_mul_f32_e32 v108, v108, v249
	v_mul_f32_e32 v109, v109, v249
	v_mul_f32_e32 v172, 0xbfb8aa3b, v110
	v_mul_f32_e32 v173, 0xbfb8aa3b, v111
	v_mul_f32_e32 v174, 0xbfb8aa3b, v112
	v_mul_f32_e32 v175, 0xbfb8aa3b, v113
	v_exp_f32_e32 v172, v172
	v_exp_f32_e32 v173, v173
	v_exp_f32_e32 v174, v174
	v_exp_f32_e32 v175, v175
	v_mul_f32_e32 v106, v110, v106
	v_mul_f32_e32 v107, v111, v107
	v_mul_f32_e32 v108, v112, v108
	v_mul_f32_e32 v109, v113, v109
	v_add_f32_e32 v172, 1.0, v172
	v_add_f32_e32 v173, 1.0, v173
	v_add_f32_e32 v174, 1.0, v174
	v_add_f32_e32 v175, 1.0, v175
	v_rcp_f32_e32 v172, v172
	v_rcp_f32_e32 v173, v173
	v_rcp_f32_e32 v174, v174
	v_rcp_f32_e32 v175, v175
	v_mul_f32_e32 v110, v106, v172
	v_mul_f32_e32 v111, v107, v173
	v_mul_f32_e32 v112, v108, v174
	v_mul_f32_e32 v113, v109, v175
	v_mul_f32_e32 v102, v102, v249
	v_mul_f32_e32 v103, v103, v249
	v_mul_f32_e32 v104, v104, v249
	v_mul_f32_e32 v105, v105, v249
	v_mul_f32_e32 v98, v98, v249
	v_mul_f32_e32 v99, v99, v249
	v_mul_f32_e32 v100, v100, v249
	v_mul_f32_e32 v101, v101, v249
	v_mul_f32_e32 v172, 0xbfb8aa3b, v102
	v_mul_f32_e32 v173, 0xbfb8aa3b, v103
	v_mul_f32_e32 v174, 0xbfb8aa3b, v104
	v_mul_f32_e32 v175, 0xbfb8aa3b, v105
	v_exp_f32_e32 v172, v172
	v_exp_f32_e32 v173, v173
	v_exp_f32_e32 v174, v174
	v_exp_f32_e32 v175, v175
	v_mul_f32_e32 v98, v102, v98
	v_mul_f32_e32 v99, v103, v99
	v_mul_f32_e32 v100, v104, v100
	v_mul_f32_e32 v101, v105, v101
	v_add_f32_e32 v172, 1.0, v172
	v_add_f32_e32 v173, 1.0, v173
	v_add_f32_e32 v174, 1.0, v174
	v_add_f32_e32 v175, 1.0, v175
	v_rcp_f32_e32 v172, v172
	v_rcp_f32_e32 v173, v173
	v_rcp_f32_e32 v174, v174
	v_rcp_f32_e32 v175, v175
	v_mul_f32_e32 v102, v98, v172
	v_mul_f32_e32 v103, v99, v173
	v_mul_f32_e32 v104, v100, v174
	v_mul_f32_e32 v105, v101, v175
	v_cvt_pk_bf16_f32 v110, v110, v111
	v_cvt_pk_bf16_f32 v111, v112, v113
	v_cvt_pk_bf16_f32 v112, v102, v103
	v_cvt_pk_bf16_f32 v113, v104, v105
	v_add_u32_e32 v171, 0x16000, v155
	global_store_dwordx4 v171, v[110:113], s[20:21] nt
	v_mul_f32_e32 v94, v94, v250
	v_mul_f32_e32 v95, v95, v250
	v_mul_f32_e32 v96, v96, v250
	v_mul_f32_e32 v97, v97, v250
	v_mul_f32_e32 v90, v90, v250
	v_mul_f32_e32 v91, v91, v250
	v_mul_f32_e32 v92, v92, v250
	v_mul_f32_e32 v93, v93, v250
	v_mul_f32_e32 v172, 0xbfb8aa3b, v94
	v_mul_f32_e32 v173, 0xbfb8aa3b, v95
	v_mul_f32_e32 v174, 0xbfb8aa3b, v96
	v_mul_f32_e32 v175, 0xbfb8aa3b, v97
	v_exp_f32_e32 v172, v172
	v_exp_f32_e32 v173, v173
	v_exp_f32_e32 v174, v174
	v_exp_f32_e32 v175, v175
	v_mul_f32_e32 v90, v94, v90
	v_mul_f32_e32 v91, v95, v91
	v_mul_f32_e32 v92, v96, v92
	v_mul_f32_e32 v93, v97, v93
	v_add_f32_e32 v172, 1.0, v172
	v_add_f32_e32 v173, 1.0, v173
	v_add_f32_e32 v174, 1.0, v174
	v_add_f32_e32 v175, 1.0, v175
	v_rcp_f32_e32 v172, v172
	v_rcp_f32_e32 v173, v173
	v_rcp_f32_e32 v174, v174
	v_rcp_f32_e32 v175, v175
	v_mul_f32_e32 v94, v90, v172
	v_mul_f32_e32 v95, v91, v173
	v_mul_f32_e32 v96, v92, v174
	v_mul_f32_e32 v97, v93, v175
	v_mul_f32_e32 v86, v86, v250
	v_mul_f32_e32 v87, v87, v250
	v_mul_f32_e32 v88, v88, v250
; __device__ __forceinline__ unsigned cvt_pk_bf16(float lo, float hi) { const f32x2 v = {lo, hi}; const pg8_bf16x2 b = __builtin_convertvector(v, pg8_bf16x2); return __builtin_bit_cast(unsigned, b); }
;     __device__ __forceinline__ void operator()(const f32x4 (&acc)[2][2][4][2], const Unit& u, int wr, int wc, int fr, int fq) const {
;     ...
;         for (int ai = 0; ai < 2; ++ai)
; #pragma unroll
;             for (int m = 0; m < 4; ++m) {
;                 const float r = rs[ai][m]; f32x4 h[2];
; #pragma unroll
;                 for (int n = 0; n < 2; ++n) { const f32x4 g = acc[ai][0][m][n] * r, up = acc[ai][1][m][n] * r;
; #pragma unroll
;                     for (int i = 0; i < 4; ++i) h[n][i] = g[i] * up[i] * __builtin_amdgcn_rcpf(1.0f + __builtin_amdgcn_exp2f(-1.4426950408889634f * g[i])); }
;                 u32x4 w; w.x = cvt_pk_bf16(h[0][0], h[0][1]); w.y = cvt_pk_bf16(h[0][2], h[0][3]); w.z = cvt_pk_bf16(h[1][0], h[1][1]); w.w = cvt_pk_bf16(h[1][2], h[1][3]);
;                 *(u32x4*)(H + (size_t)(row0 + ai * HALF + m * 16) * 2816 + u.pn * HALF + wc * 32 + 8 * fq) = w;
	v_mul_f32_e32 v89, v89, v250
	v_mul_f32_e32 v82, v82, v250
	v_mul_f32_e32 v83, v83, v250
	v_mul_f32_e32 v84, v84, v250
	v_mul_f32_e32 v85, v85, v250
	v_mul_f32_e32 v172, 0xbfb8aa3b, v86
	v_mul_f32_e32 v173, 0xbfb8aa3b, v87
	v_mul_f32_e32 v174, 0xbfb8aa3b, v88
	v_mul_f32_e32 v175, 0xbfb8aa3b, v89
	v_exp_f32_e32 v172, v172
	v_exp_f32_e32 v173, v173
	v_exp_f32_e32 v174, v174
	v_exp_f32_e32 v175, v175
	v_mul_f32_e32 v82, v86, v82
	v_mul_f32_e32 v83, v87, v83
	v_mul_f32_e32 v84, v88, v84
	v_mul_f32_e32 v85, v89, v85
	v_add_f32_e32 v172, 1.0, v172
	v_add_f32_e32 v173, 1.0, v173
	v_add_f32_e32 v174, 1.0, v174
	v_add_f32_e32 v175, 1.0, v175
	v_rcp_f32_e32 v172, v172
	v_rcp_f32_e32 v173, v173
	v_rcp_f32_e32 v174, v174
	v_rcp_f32_e32 v175, v175
	v_mul_f32_e32 v86, v82, v172
	v_mul_f32_e32 v87, v83, v173
	v_mul_f32_e32 v88, v84, v174
	v_mul_f32_e32 v89, v85, v175
	v_cvt_pk_bf16_f32 v94, v94, v95
	v_cvt_pk_bf16_f32 v95, v96, v97
	v_cvt_pk_bf16_f32 v96, v86, v87
	v_cvt_pk_bf16_f32 v97, v88, v89
	v_add_u32_e32 v170, 0x2c000, v155
	global_store_dwordx4 v170, v[94:97], s[20:21] nt
	v_mul_f32_e32 v76, v76, v251
	v_mul_f32_e32 v77, v77, v251
	v_mul_f32_e32 v78, v78, v251
	v_mul_f32_e32 v79, v79, v251
	v_mul_f32_e32 v72, v72, v251
	v_mul_f32_e32 v73, v73, v251
	v_mul_f32_e32 v74, v74, v251
	v_mul_f32_e32 v75, v75, v251
	v_mul_f32_e32 v172, 0xbfb8aa3b, v76
	v_mul_f32_e32 v173, 0xbfb8aa3b, v77
	v_mul_f32_e32 v174, 0xbfb8aa3b, v78
	v_mul_f32_e32 v175, 0xbfb8aa3b, v79
	v_exp_f32_e32 v172, v172
	v_exp_f32_e32 v173, v173
	v_exp_f32_e32 v174, v174
	v_exp_f32_e32 v175, v175
	v_mul_f32_e32 v72, v76, v72
	v_mul_f32_e32 v73, v77, v73
	v_mul_f32_e32 v74, v78, v74
	v_mul_f32_e32 v75, v79, v75
	v_add_f32_e32 v172, 1.0, v172
	v_add_f32_e32 v173, 1.0, v173
	v_add_f32_e32 v174, 1.0, v174
	v_add_f32_e32 v175, 1.0, v175
	v_rcp_f32_e32 v172, v172
	v_rcp_f32_e32 v173, v173
	v_rcp_f32_e32 v174, v174
	v_rcp_f32_e32 v175, v175
	v_mul_f32_e32 v76, v72, v172
	v_mul_f32_e32 v77, v73, v173
	v_mul_f32_e32 v78, v74, v174
	v_mul_f32_e32 v79, v75, v175
	v_mul_f32_e32 v68, v68, v251
	v_mul_f32_e32 v69, v69, v251
	v_mul_f32_e32 v70, v70, v251
	v_mul_f32_e32 v71, v71, v251
	v_mul_f32_e32 v64, v64, v251
	v_mul_f32_e32 v65, v65, v251
	v_mul_f32_e32 v66, v66, v251
	v_mul_f32_e32 v67, v67, v251
	v_mul_f32_e32 v172, 0xbfb8aa3b, v68
	v_mul_f32_e32 v173, 0xbfb8aa3b, v69
	v_mul_f32_e32 v174, 0xbfb8aa3b, v70
	v_mul_f32_e32 v175, 0xbfb8aa3b, v71
	v_exp_f32_e32 v172, v172
	v_exp_f32_e32 v173, v173
	v_exp_f32_e32 v174, v174
	v_exp_f32_e32 v175, v175
	v_mul_f32_e32 v64, v68, v64
	v_mul_f32_e32 v65, v69, v65
	v_mul_f32_e32 v66, v70, v66
	v_mul_f32_e32 v67, v71, v67
	v_add_f32_e32 v172, 1.0, v172
	v_add_f32_e32 v173, 1.0, v173
	v_add_f32_e32 v174, 1.0, v174
	v_add_f32_e32 v175, 1.0, v175
	v_rcp_f32_e32 v172, v172
	v_rcp_f32_e32 v173, v173
	v_rcp_f32_e32 v174, v174
	v_rcp_f32_e32 v175, v175
	v_mul_f32_e32 v68, v64, v172
	v_mul_f32_e32 v69, v65, v173
	v_mul_f32_e32 v70, v66, v174
	v_mul_f32_e32 v71, v67, v175
	v_cvt_pk_bf16_f32 v76, v76, v77
	v_cvt_pk_bf16_f32 v77, v78, v79
	v_cvt_pk_bf16_f32 v78, v68, v69
	v_cvt_pk_bf16_f32 v79, v70, v71
	v_add_u32_e32 v171, 0x42000, v155
	global_store_dwordx4 v171, v[76:79], s[20:21] nt
	v_mul_f32_e32 v60, v60, v252
	v_mul_f32_e32 v61, v61, v252
	v_mul_f32_e32 v62, v62, v252
	v_mul_f32_e32 v63, v63, v252
	v_mul_f32_e32 v56, v56, v252
	v_mul_f32_e32 v57, v57, v252
	v_mul_f32_e32 v58, v58, v252
	v_mul_f32_e32 v59, v59, v252
	v_mul_f32_e32 v172, 0xbfb8aa3b, v60
	v_mul_f32_e32 v173, 0xbfb8aa3b, v61
	v_mul_f32_e32 v174, 0xbfb8aa3b, v62
	v_mul_f32_e32 v175, 0xbfb8aa3b, v63
	v_exp_f32_e32 v172, v172
	v_exp_f32_e32 v173, v173
	v_exp_f32_e32 v174, v174
	v_exp_f32_e32 v175, v175
	v_mul_f32_e32 v56, v60, v56
	v_mul_f32_e32 v57, v61, v57
	v_mul_f32_e32 v58, v62, v58
	v_mul_f32_e32 v59, v63, v59
	v_add_f32_e32 v172, 1.0, v172
	v_add_f32_e32 v173, 1.0, v173
	v_add_f32_e32 v174, 1.0, v174
	v_add_f32_e32 v175, 1.0, v175
	v_rcp_f32_e32 v172, v172
	v_rcp_f32_e32 v173, v173
	v_rcp_f32_e32 v174, v174
	v_rcp_f32_e32 v175, v175
	v_mul_f32_e32 v60, v56, v172
	v_mul_f32_e32 v61, v57, v173
	v_mul_f32_e32 v62, v58, v174
	v_mul_f32_e32 v63, v59, v175
	v_mul_f32_e32 v52, v52, v252
	v_mul_f32_e32 v53, v53, v252
	v_mul_f32_e32 v54, v54, v252
	v_mul_f32_e32 v55, v55, v252
	v_mul_f32_e32 v48, v48, v252
	v_mul_f32_e32 v49, v49, v252
	v_mul_f32_e32 v50, v50, v252
	v_mul_f32_e32 v51, v51, v252
	v_mul_f32_e32 v172, 0xbfb8aa3b, v52
	v_mul_f32_e32 v173, 0xbfb8aa3b, v53
	v_mul_f32_e32 v174, 0xbfb8aa3b, v54
	v_mul_f32_e32 v175, 0xbfb8aa3b, v55
	v_exp_f32_e32 v172, v172
	v_exp_f32_e32 v173, v173
	v_exp_f32_e32 v174, v174
	v_exp_f32_e32 v175, v175
	v_mul_f32_e32 v48, v52, v48
	v_mul_f32_e32 v49, v53, v49
	v_mul_f32_e32 v50, v54, v50
	v_mul_f32_e32 v51, v55, v51
	v_add_f32_e32 v172, 1.0, v172
	v_add_f32_e32 v173, 1.0, v173
	v_add_f32_e32 v174, 1.0, v174
	v_add_f32_e32 v175, 1.0, v175
	v_rcp_f32_e32 v172, v172
	v_rcp_f32_e32 v173, v173
	v_rcp_f32_e32 v174, v174
	v_rcp_f32_e32 v175, v175
	v_mul_f32_e32 v52, v48, v172
	v_mul_f32_e32 v53, v49, v173
	v_mul_f32_e32 v54, v50, v174
	v_mul_f32_e32 v55, v51, v175
	v_cvt_pk_bf16_f32 v60, v60, v61
	v_cvt_pk_bf16_f32 v61, v62, v63
	v_cvt_pk_bf16_f32 v62, v52, v53
	v_cvt_pk_bf16_f32 v63, v54, v55
	v_add_u32_e32 v170, 0xb0000, v155
	global_store_dwordx4 v170, v[60:63], s[20:21] nt
	v_mul_f32_e32 v44, v44, v253
	v_mul_f32_e32 v45, v45, v253
	v_mul_f32_e32 v46, v46, v253
	v_mul_f32_e32 v47, v47, v253
	v_mul_f32_e32 v40, v40, v253
	v_mul_f32_e32 v41, v41, v253
	v_mul_f32_e32 v42, v42, v253
	v_mul_f32_e32 v43, v43, v253
	v_mul_f32_e32 v172, 0xbfb8aa3b, v44
	v_mul_f32_e32 v173, 0xbfb8aa3b, v45
; __device__ __forceinline__ unsigned cvt_pk_bf16(float lo, float hi) { const f32x2 v = {lo, hi}; const pg8_bf16x2 b = __builtin_convertvector(v, pg8_bf16x2); return __builtin_bit_cast(unsigned, b); }
;     __device__ __forceinline__ void operator()(const f32x4 (&acc)[2][2][4][2], const Unit& u, int wr, int wc, int fr, int fq) const {
;     ...
;         for (int ai = 0; ai < 2; ++ai)
; #pragma unroll
;             for (int m = 0; m < 4; ++m) {
;                 const float r = rs[ai][m]; f32x4 h[2];
; #pragma unroll
;                 for (int n = 0; n < 2; ++n) { const f32x4 g = acc[ai][0][m][n] * r, up = acc[ai][1][m][n] * r;
; #pragma unroll
;                     for (int i = 0; i < 4; ++i) h[n][i] = g[i] * up[i] * __builtin_amdgcn_rcpf(1.0f + __builtin_amdgcn_exp2f(-1.4426950408889634f * g[i])); }
;                 u32x4 w; w.x = cvt_pk_bf16(h[0][0], h[0][1]); w.y = cvt_pk_bf16(h[0][2], h[0][3]); w.z = cvt_pk_bf16(h[1][0], h[1][1]); w.w = cvt_pk_bf16(h[1][2], h[1][3]);
;                 *(u32x4*)(H + (size_t)(row0 + ai * HALF + m * 16) * 2816 + u.pn * HALF + wc * 32 + 8 * fq) = w;
	v_mul_f32_e32 v174, 0xbfb8aa3b, v46
	v_mul_f32_e32 v175, 0xbfb8aa3b, v47
	v_exp_f32_e32 v172, v172
	v_exp_f32_e32 v173, v173
	v_exp_f32_e32 v174, v174
	v_exp_f32_e32 v175, v175
	v_mul_f32_e32 v40, v44, v40
	v_mul_f32_e32 v41, v45, v41
	v_mul_f32_e32 v42, v46, v42
	v_mul_f32_e32 v43, v47, v43
	v_add_f32_e32 v172, 1.0, v172
	v_add_f32_e32 v173, 1.0, v173
	v_add_f32_e32 v174, 1.0, v174
	v_add_f32_e32 v175, 1.0, v175
	v_rcp_f32_e32 v172, v172
	v_rcp_f32_e32 v173, v173
	v_rcp_f32_e32 v174, v174
	v_rcp_f32_e32 v175, v175
	v_mul_f32_e32 v44, v40, v172
	v_mul_f32_e32 v45, v41, v173
	v_mul_f32_e32 v46, v42, v174
	v_mul_f32_e32 v47, v43, v175
	v_mul_f32_e32 v36, v36, v253
	v_mul_f32_e32 v37, v37, v253
	v_mul_f32_e32 v38, v38, v253
	v_mul_f32_e32 v39, v39, v253
	v_mul_f32_e32 v32, v32, v253
	v_mul_f32_e32 v33, v33, v253
	v_mul_f32_e32 v34, v34, v253
	v_mul_f32_e32 v35, v35, v253
	v_mul_f32_e32 v172, 0xbfb8aa3b, v36
	v_mul_f32_e32 v173, 0xbfb8aa3b, v37
	v_mul_f32_e32 v174, 0xbfb8aa3b, v38
	v_mul_f32_e32 v175, 0xbfb8aa3b, v39
	v_exp_f32_e32 v172, v172
	v_exp_f32_e32 v173, v173
	v_exp_f32_e32 v174, v174
	v_exp_f32_e32 v175, v175
	v_mul_f32_e32 v32, v36, v32
	v_mul_f32_e32 v33, v37, v33
	v_mul_f32_e32 v34, v38, v34
	v_mul_f32_e32 v35, v39, v35
	v_add_f32_e32 v172, 1.0, v172
	v_add_f32_e32 v173, 1.0, v173
	v_add_f32_e32 v174, 1.0, v174
	v_add_f32_e32 v175, 1.0, v175
	v_rcp_f32_e32 v172, v172
	v_rcp_f32_e32 v173, v173
	v_rcp_f32_e32 v174, v174
	v_rcp_f32_e32 v175, v175
	v_mul_f32_e32 v36, v32, v172
	v_mul_f32_e32 v37, v33, v173
	v_mul_f32_e32 v38, v34, v174
	v_mul_f32_e32 v39, v35, v175
	v_cvt_pk_bf16_f32 v44, v44, v45
	v_cvt_pk_bf16_f32 v45, v46, v47
	v_cvt_pk_bf16_f32 v46, v36, v37
	v_cvt_pk_bf16_f32 v47, v38, v39
	v_add_u32_e32 v171, 0xc6000, v155
	global_store_dwordx4 v171, v[44:47], s[20:21] nt
	v_mul_f32_e32 v28, v28, v254
	v_mul_f32_e32 v29, v29, v254
	v_mul_f32_e32 v30, v30, v254
	v_mul_f32_e32 v31, v31, v254
	v_mul_f32_e32 v24, v24, v254
	v_mul_f32_e32 v25, v25, v254
	v_mul_f32_e32 v26, v26, v254
	v_mul_f32_e32 v27, v27, v254
	v_mul_f32_e32 v172, 0xbfb8aa3b, v28
	v_mul_f32_e32 v173, 0xbfb8aa3b, v29
	v_mul_f32_e32 v174, 0xbfb8aa3b, v30
	v_mul_f32_e32 v175, 0xbfb8aa3b, v31
	v_exp_f32_e32 v172, v172
	v_exp_f32_e32 v173, v173
	v_exp_f32_e32 v174, v174
	v_exp_f32_e32 v175, v175
	v_mul_f32_e32 v24, v28, v24
	v_mul_f32_e32 v25, v29, v25
	v_mul_f32_e32 v26, v30, v26
	v_mul_f32_e32 v27, v31, v27
	v_add_f32_e32 v172, 1.0, v172
	v_add_f32_e32 v173, 1.0, v173
	v_add_f32_e32 v174, 1.0, v174
	v_add_f32_e32 v175, 1.0, v175
	v_rcp_f32_e32 v172, v172
	v_rcp_f32_e32 v173, v173
	v_rcp_f32_e32 v174, v174
	v_rcp_f32_e32 v175, v175
	v_mul_f32_e32 v28, v24, v172
	v_mul_f32_e32 v29, v25, v173
	v_mul_f32_e32 v30, v26, v174
	v_mul_f32_e32 v31, v27, v175
	v_mul_f32_e32 v20, v20, v254
	v_mul_f32_e32 v21, v21, v254
	v_mul_f32_e32 v22, v22, v254
	v_mul_f32_e32 v23, v23, v254
	v_mul_f32_e32 v16, v16, v254
	v_mul_f32_e32 v17, v17, v254
	v_mul_f32_e32 v18, v18, v254
	v_mul_f32_e32 v19, v19, v254
	v_mul_f32_e32 v172, 0xbfb8aa3b, v20
	v_mul_f32_e32 v173, 0xbfb8aa3b, v21
	v_mul_f32_e32 v174, 0xbfb8aa3b, v22
	v_mul_f32_e32 v175, 0xbfb8aa3b, v23
	v_exp_f32_e32 v172, v172
	v_exp_f32_e32 v173, v173
	v_exp_f32_e32 v174, v174
	v_exp_f32_e32 v175, v175
	v_mul_f32_e32 v16, v20, v16
	v_mul_f32_e32 v17, v21, v17
	v_mul_f32_e32 v18, v22, v18
	v_mul_f32_e32 v19, v23, v19
	v_add_f32_e32 v172, 1.0, v172
	v_add_f32_e32 v173, 1.0, v173
	v_add_f32_e32 v174, 1.0, v174
	v_add_f32_e32 v175, 1.0, v175
	v_rcp_f32_e32 v172, v172
	v_rcp_f32_e32 v173, v173
	v_rcp_f32_e32 v174, v174
	v_rcp_f32_e32 v175, v175
	v_mul_f32_e32 v20, v16, v172
	v_mul_f32_e32 v21, v17, v173
	v_mul_f32_e32 v22, v18, v174
	v_mul_f32_e32 v23, v19, v175
	v_cvt_pk_bf16_f32 v28, v28, v29
	v_cvt_pk_bf16_f32 v29, v30, v31
	v_cvt_pk_bf16_f32 v30, v20, v21
	v_cvt_pk_bf16_f32 v31, v22, v23
	v_add_u32_e32 v170, 0xdc000, v155
	global_store_dwordx4 v170, v[28:31], s[20:21] nt
	v_mul_f32_e32 v12, v12, v255
	v_mul_f32_e32 v13, v13, v255
	v_mul_f32_e32 v14, v14, v255
	v_mul_f32_e32 v15, v15, v255
	v_mul_f32_e32 v8, v8, v255
	v_mul_f32_e32 v9, v9, v255
	v_mul_f32_e32 v10, v10, v255
	v_mul_f32_e32 v11, v11, v255
	v_mul_f32_e32 v172, 0xbfb8aa3b, v12
	v_mul_f32_e32 v173, 0xbfb8aa3b, v13
	v_mul_f32_e32 v174, 0xbfb8aa3b, v14
	v_mul_f32_e32 v175, 0xbfb8aa3b, v15
	v_exp_f32_e32 v172, v172
	v_exp_f32_e32 v173, v173
	v_exp_f32_e32 v174, v174
	v_exp_f32_e32 v175, v175
	v_mul_f32_e32 v8, v12, v8
	v_mul_f32_e32 v9, v13, v9
	v_mul_f32_e32 v10, v14, v10
	v_mul_f32_e32 v11, v15, v11
	v_add_f32_e32 v172, 1.0, v172
	v_add_f32_e32 v173, 1.0, v173
	v_add_f32_e32 v174, 1.0, v174
	v_add_f32_e32 v175, 1.0, v175
	v_rcp_f32_e32 v172, v172
	v_rcp_f32_e32 v173, v173
	v_rcp_f32_e32 v174, v174
	v_rcp_f32_e32 v175, v175
	v_mul_f32_e32 v12, v8, v172
	v_mul_f32_e32 v13, v9, v173
	v_mul_f32_e32 v14, v10, v174
	v_mul_f32_e32 v15, v11, v175
	v_mul_f32_e32 v4, v4, v255
	v_mul_f32_e32 v5, v5, v255
	v_mul_f32_e32 v6, v6, v255
	v_mul_f32_e32 v7, v7, v255
	v_mul_f32_e32 v0, v0, v255
	v_mul_f32_e32 v1, v1, v255
	v_mul_f32_e32 v2, v2, v255
	v_mul_f32_e32 v3, v3, v255
	v_mul_f32_e32 v172, 0xbfb8aa3b, v4
	v_mul_f32_e32 v173, 0xbfb8aa3b, v5
	v_mul_f32_e32 v174, 0xbfb8aa3b, v6
	v_mul_f32_e32 v175, 0xbfb8aa3b, v7
	v_exp_f32_e32 v172, v172
	v_exp_f32_e32 v173, v173
	v_exp_f32_e32 v174, v174
	v_exp_f32_e32 v175, v175
	v_mul_f32_e32 v0, v4, v0
	v_mul_f32_e32 v1, v5, v1
	v_mul_f32_e32 v2, v6, v2
	v_mul_f32_e32 v3, v7, v3
	v_add_f32_e32 v172, 1.0, v172
	v_add_f32_e32 v173, 1.0, v173
	v_add_f32_e32 v174, 1.0, v174
	v_add_f32_e32 v175, 1.0, v175
	v_rcp_f32_e32 v172, v172
	v_rcp_f32_e32 v173, v173
	v_rcp_f32_e32 v174, v174
	v_rcp_f32_e32 v175, v175
	v_mul_f32_e32 v4, v0, v172
	v_mul_f32_e32 v5, v1, v173
	v_mul_f32_e32 v6, v2, v174
	v_mul_f32_e32 v7, v3, v175
	v_cvt_pk_bf16_f32 v12, v12, v13
	v_cvt_pk_bf16_f32 v13, v14, v15
	v_cvt_pk_bf16_f32 v14, v4, v5
	v_cvt_pk_bf16_f32 v15, v6, v7
	v_add_u32_e32 v171, 0xf2000, v155
	global_store_dwordx4 v171, v[12:15], s[20:21] nt
	s_cbranch_execnz .LBB0_42
